# P0: batched loads in W1/W_in transposes and 4-deep batched ATT/COMB absorption loops (on top of XN rewrite)
# speedup vs baseline: 1.0210x; 1.0210x over previous
_Z6mk_fwd4Args:
	s_load_dwordx4 s[28:31], s[0:1], 0xa0
	s_add_u32 s4, s0, 0xa8
	s_addc_u32 s5, s1, 0
	v_and_b32_e32 v209, 0x3ff, v0
	s_waitcnt lgkmcnt(0)
	s_and_b32 s3, s30, 7
	v_readfirstlane_b32 s34, v209
	s_cmp_lg_u32 s3, 0
	s_mov_b32 s3, s2
	s_cbranch_scc1 .LBB0_2
	s_ashr_i32 s6, s2, 31
	s_lshr_b32 s6, s6, 29
	s_add_i32 s6, s2, s6
	s_and_b32 s7, s6, -8
	s_ashr_i32 s3, s30, 3
	s_sub_i32 s7, s2, s7
	s_mul_i32 s3, s3, s7
	s_ashr_i32 s6, s6, 3
	s_add_i32 s3, s3, s6

.LBB0_29:
	s_cmpk_gt_i32 s34, 0x5ff
	s_mov_b64 s[0:1], -1
	s_cbranch_scc0 .LBB0_101
	s_cmpk_gt_u32 s34, 0x63f
	s_cbranch_scc0 .LBB0_80
	s_cmpk_gt_u32 s34, 0x83f
	s_cbranch_scc0 .LBB0_75
	s_lshl_b32 s0, s65, 2
	s_and_b32 s0, s0, 0xf00
	v_lshl_or_b32 v0, v203, 2, s0
	v_mov_b32_e32 v1, v45
	s_cmpk_gt_u32 s34, 0x103f
	s_mov_b64 s[0:1], -1
	s_cbranch_scc0 .LBB0_70
	s_cmpk_gt_u32 s34, 0x123f
	s_cbranch_scc0 .LBB0_65
	s_cmpk_gt_u32 s34, 0x1a3f
	s_cbranch_scc0 .LBB0_44
	s_cmpk_gt_u32 s34, 0x223f
	s_cbranch_scc0 .LBB0_39
	s_lshr_b32 s4, s80, 8
	v_readlane_b32 s12, v244, 0
	s_lshl_b64 s[0:1], s[4:5], 19
	v_readlane_b32 s26, v244, 14
	v_readlane_b32 s27, v244, 15
	s_add_u32 s0, s26, s0
	s_addc_u32 s1, s27, s1
	v_readlane_b32 s24, v244, 12
	v_lshl_add_u64 v[2:3], s[0:1], 0, v[0:1]
	s_lshl_b64 s[0:1], s[4:5], 9
	v_readlane_b32 s25, v244, 13
	s_add_u32 s4, s24, s0
	s_addc_u32 s10, s25, s1
	s_lshl_b64 s[0:1], s[80:81], 8
	v_readlane_b32 s22, v244, 10
	s_and_b32 s1, s1, 0xff
	s_and_b32 s0, s0, 0xfffff000
	v_readlane_b32 s23, v244, 11
	s_add_u32 s11, s22, s0
	v_mov_b32_e32 v4, 0
	s_addc_u32 s88, s23, s1
	s_mov_b64 s[0:1], 0
	v_mov_b32_e32 v5, v4
	v_mov_b32_e32 v6, v4
	v_mov_b32_e32 v8, v4
	v_mov_b32_e32 v7, v4
	v_mov_b32_e32 v9, v4
	v_mov_b32_e32 v10, v4
	v_mov_b32_e32 v11, v4
	v_readlane_b32 s13, v244, 1
	v_readlane_b32 s14, v244, 2
	v_readlane_b32 s15, v244, 3
	v_readlane_b32 s16, v244, 4
	v_readlane_b32 s17, v244, 5
	v_readlane_b32 s18, v244, 6
	v_readlane_b32 s19, v244, 7
	v_readlane_b32 s20, v244, 8
	v_readlane_b32 s21, v244, 9
	s_mov_b64 s[14:15], 0x2000
	s_mov_b64 s[16:17], 0x3000
.Lcomb_loop:
	s_add_u32 s68, s4, s0
	s_addc_u32 s69, s10, s1
	s_add_u32 s12, s11, s0
	s_addc_u32 s13, s88, s1
	v_lshl_add_u64 v[62:63], v[2:3], 0, s[14:15]
	v_lshl_add_u64 v[64:65], v[2:3], 0, s[16:17]
	global_load_dword v16, v[2:3], off
	global_load_dword v17, v[62:63], off offset:-4096
	global_load_dword v18, v[62:63], off
	global_load_dword v19, v[64:65], off
	v_lshl_add_u64 v[2:3], v[2:3], 0, s[86:87]
	global_load_dwordx4 v[12:15], v45, s[68:69]
	global_load_dwordx4 v[104:107], v45, s[12:13]
	global_load_dwordx4 v[108:111], v45, s[12:13] offset:512
	global_load_dwordx4 v[112:115], v45, s[12:13] offset:1024
	global_load_dwordx4 v[116:119], v45, s[12:13] offset:1536
	global_load_dwordx4 v[120:123], v45, s[12:13] offset:2048
	global_load_dwordx4 v[124:127], v45, s[12:13] offset:2560
	global_load_dwordx4 v[128:131], v45, s[12:13] offset:3072
	global_load_dwordx4 v[132:135], v45, s[12:13] offset:3584
	v_lshl_add_u64 v[62:63], v[2:3], 0, s[14:15]
	v_lshl_add_u64 v[64:65], v[2:3], 0, s[16:17]
	global_load_dword v24, v[2:3], off
	global_load_dword v25, v[62:63], off offset:-4096
	global_load_dword v26, v[62:63], off
	global_load_dword v27, v[64:65], off
	v_lshl_add_u64 v[2:3], v[2:3], 0, s[86:87]
	global_load_dwordx4 v[20:23], v45, s[68:69] offset:16
	global_load_dwordx4 v[138:141], v45, s[12:13] offset:16
	global_load_dwordx4 v[142:145], v45, s[12:13] offset:528
	global_load_dwordx4 v[146:149], v45, s[12:13] offset:1040
	global_load_dwordx4 v[150:153], v45, s[12:13] offset:1552
	global_load_dwordx4 v[154:157], v45, s[12:13] offset:2064
	global_load_dwordx4 v[158:161], v45, s[12:13] offset:2576
	global_load_dwordx4 v[162:165], v45, s[12:13] offset:3088
	global_load_dwordx4 v[166:169], v45, s[12:13] offset:3600
	v_lshl_add_u64 v[62:63], v[2:3], 0, s[14:15]
	v_lshl_add_u64 v[64:65], v[2:3], 0, s[16:17]
	global_load_dword v32, v[2:3], off
	global_load_dword v33, v[62:63], off offset:-4096
	global_load_dword v34, v[62:63], off
	global_load_dword v35, v[64:65], off
	v_lshl_add_u64 v[2:3], v[2:3], 0, s[86:87]
	global_load_dwordx4 v[28:31], v45, s[68:69] offset:32
	global_load_dwordx4 v[170:173], v45, s[12:13] offset:32
	global_load_dwordx4 v[174:177], v45, s[12:13] offset:544
	global_load_dwordx4 v[178:181], v45, s[12:13] offset:1056
	global_load_dwordx4 v[182:185], v45, s[12:13] offset:1568
	global_load_dwordx4 v[186:189], v45, s[12:13] offset:2080
	global_load_dwordx4 v[190:193], v45, s[12:13] offset:2592
	global_load_dwordx4 v[194:197], v45, s[12:13] offset:3104
	global_load_dwordx4 v[198:201], v45, s[12:13] offset:3616
	v_lshl_add_u64 v[62:63], v[2:3], 0, s[14:15]
	v_lshl_add_u64 v[64:65], v[2:3], 0, s[16:17]
	global_load_dword v58, v[2:3], off
	global_load_dword v59, v[62:63], off offset:-4096
	global_load_dword v60, v[62:63], off
	global_load_dword v61, v[64:65], off
	v_lshl_add_u64 v[2:3], v[2:3], 0, s[86:87]
	global_load_dwordx4 v[36:39], v45, s[68:69] offset:48
	global_load_dwordx4 v[210:213], v45, s[12:13] offset:48
	global_load_dwordx4 v[214:217], v45, s[12:13] offset:560
	global_load_dwordx4 v[218:221], v45, s[12:13] offset:1072
	global_load_dwordx4 v[222:225], v45, s[12:13] offset:1584
	global_load_dwordx4 v[226:229], v45, s[12:13] offset:2096
	global_load_dwordx4 v[230:233], v45, s[12:13] offset:2608
	global_load_dwordx4 v[234:237], v45, s[12:13] offset:3120
	global_load_dwordx4 v[238:241], v45, s[12:13] offset:3632
	s_add_u32 s0, s0, 64
	s_addc_u32 s1, s1, 0
	s_waitcnt vmcnt(39)
	v_mul_f32_e32 v16, v16, v12
	v_mul_f32_e32 v17, v17, v13
	v_mul_f32_e32 v18, v18, v14
	v_mul_f32_e32 v19, v19, v15
	v_fmac_f32_e32 v6, v16, v104
	v_fmac_f32_e32 v8, v16, v108
	v_fmac_f32_e32 v7, v16, v112
	v_fmac_f32_e32 v9, v16, v116
	v_fmac_f32_e32 v4, v16, v120
	v_fmac_f32_e32 v10, v16, v124
	v_fmac_f32_e32 v5, v16, v128
	v_fmac_f32_e32 v11, v16, v132
	v_fmac_f32_e32 v6, v17, v105
	v_fmac_f32_e32 v8, v17, v109
	v_fmac_f32_e32 v7, v17, v113
	v_fmac_f32_e32 v9, v17, v117
	v_fmac_f32_e32 v4, v17, v121
	v_fmac_f32_e32 v10, v17, v125
	v_fmac_f32_e32 v5, v17, v129
	v_fmac_f32_e32 v11, v17, v133
	v_fmac_f32_e32 v6, v18, v106
	v_fmac_f32_e32 v8, v18, v110
	v_fmac_f32_e32 v7, v18, v114
	v_fmac_f32_e32 v9, v18, v118
	v_fmac_f32_e32 v4, v18, v122
	v_fmac_f32_e32 v10, v18, v126
	v_fmac_f32_e32 v5, v18, v130
	v_fmac_f32_e32 v11, v18, v134
	v_fmac_f32_e32 v6, v19, v107
	v_fmac_f32_e32 v8, v19, v111
	v_fmac_f32_e32 v7, v19, v115
	v_fmac_f32_e32 v9, v19, v119
	v_fmac_f32_e32 v4, v19, v123
	v_fmac_f32_e32 v10, v19, v127
	v_fmac_f32_e32 v5, v19, v131
	v_fmac_f32_e32 v11, v19, v135
	s_waitcnt vmcnt(26)
	v_mul_f32_e32 v24, v24, v20
	v_mul_f32_e32 v25, v25, v21
	v_mul_f32_e32 v26, v26, v22
	v_mul_f32_e32 v27, v27, v23
	v_fmac_f32_e32 v6, v24, v138
	v_fmac_f32_e32 v8, v24, v142
	v_fmac_f32_e32 v7, v24, v146
	v_fmac_f32_e32 v9, v24, v150
	v_fmac_f32_e32 v4, v24, v154
	v_fmac_f32_e32 v10, v24, v158
	v_fmac_f32_e32 v5, v24, v162
	v_fmac_f32_e32 v11, v24, v166
	v_fmac_f32_e32 v6, v25, v139
	v_fmac_f32_e32 v8, v25, v143
	v_fmac_f32_e32 v7, v25, v147
	v_fmac_f32_e32 v9, v25, v151
	v_fmac_f32_e32 v4, v25, v155
	v_fmac_f32_e32 v10, v25, v159
	v_fmac_f32_e32 v5, v25, v163
	v_fmac_f32_e32 v11, v25, v167
	v_fmac_f32_e32 v6, v26, v140
	v_fmac_f32_e32 v8, v26, v144
	v_fmac_f32_e32 v7, v26, v148
	v_fmac_f32_e32 v9, v26, v152
	v_fmac_f32_e32 v4, v26, v156
	v_fmac_f32_e32 v10, v26, v160
	v_fmac_f32_e32 v5, v26, v164
	v_fmac_f32_e32 v11, v26, v168
	v_fmac_f32_e32 v6, v27, v141
	v_fmac_f32_e32 v8, v27, v145
	v_fmac_f32_e32 v7, v27, v149
	v_fmac_f32_e32 v9, v27, v153
	v_fmac_f32_e32 v4, v27, v157
	v_fmac_f32_e32 v10, v27, v161
	v_fmac_f32_e32 v5, v27, v165
	v_fmac_f32_e32 v11, v27, v169
	s_waitcnt vmcnt(13)
	v_mul_f32_e32 v32, v32, v28
	v_mul_f32_e32 v33, v33, v29
	v_mul_f32_e32 v34, v34, v30
	v_mul_f32_e32 v35, v35, v31
	v_fmac_f32_e32 v6, v32, v170
	v_fmac_f32_e32 v8, v32, v174
	v_fmac_f32_e32 v7, v32, v178
	v_fmac_f32_e32 v9, v32, v182
	v_fmac_f32_e32 v4, v32, v186
	v_fmac_f32_e32 v10, v32, v190
	v_fmac_f32_e32 v5, v32, v194
	v_fmac_f32_e32 v11, v32, v198
	v_fmac_f32_e32 v6, v33, v171
	v_fmac_f32_e32 v8, v33, v175
	v_fmac_f32_e32 v7, v33, v179
	v_fmac_f32_e32 v9, v33, v183
	v_fmac_f32_e32 v4, v33, v187
	v_fmac_f32_e32 v10, v33, v191
	v_fmac_f32_e32 v5, v33, v195
	v_fmac_f32_e32 v11, v33, v199
	v_fmac_f32_e32 v6, v34, v172
	v_fmac_f32_e32 v8, v34, v176
	v_fmac_f32_e32 v7, v34, v180
	v_fmac_f32_e32 v9, v34, v184
	v_fmac_f32_e32 v4, v34, v188
	v_fmac_f32_e32 v10, v34, v192
	v_fmac_f32_e32 v5, v34, v196
	v_fmac_f32_e32 v11, v34, v200
	v_fmac_f32_e32 v6, v35, v173
	v_fmac_f32_e32 v8, v35, v177
	v_fmac_f32_e32 v7, v35, v181
	v_fmac_f32_e32 v9, v35, v185
	v_fmac_f32_e32 v4, v35, v189
	v_fmac_f32_e32 v10, v35, v193
	v_fmac_f32_e32 v5, v35, v197
	v_fmac_f32_e32 v11, v35, v201
	s_waitcnt vmcnt(0)
	v_mul_f32_e32 v58, v58, v36
	v_mul_f32_e32 v59, v59, v37
	v_mul_f32_e32 v60, v60, v38
	v_mul_f32_e32 v61, v61, v39
	v_fmac_f32_e32 v6, v58, v210
	v_fmac_f32_e32 v8, v58, v214
	v_fmac_f32_e32 v7, v58, v218
	v_fmac_f32_e32 v9, v58, v222
	v_fmac_f32_e32 v4, v58, v226
	v_fmac_f32_e32 v10, v58, v230
	v_fmac_f32_e32 v5, v58, v234
	v_fmac_f32_e32 v11, v58, v238
	v_fmac_f32_e32 v6, v59, v211
	v_fmac_f32_e32 v8, v59, v215
	v_fmac_f32_e32 v7, v59, v219
	v_fmac_f32_e32 v9, v59, v223
	v_fmac_f32_e32 v4, v59, v227
	v_fmac_f32_e32 v10, v59, v231
	v_fmac_f32_e32 v5, v59, v235
	v_fmac_f32_e32 v11, v59, v239
	v_fmac_f32_e32 v6, v60, v212
	v_fmac_f32_e32 v8, v60, v216
	v_fmac_f32_e32 v7, v60, v220
	v_fmac_f32_e32 v9, v60, v224
	v_fmac_f32_e32 v4, v60, v228
	v_fmac_f32_e32 v10, v60, v232
	v_fmac_f32_e32 v5, v60, v236
	v_fmac_f32_e32 v11, v60, v240
	v_fmac_f32_e32 v6, v61, v213
	v_fmac_f32_e32 v8, v61, v217
	v_fmac_f32_e32 v7, v61, v221
	v_fmac_f32_e32 v9, v61, v225
	v_fmac_f32_e32 v4, v61, v229
	v_fmac_f32_e32 v10, v61, v233
	v_fmac_f32_e32 v5, v61, v237
	v_fmac_f32_e32 v11, v61, v241
	s_cmpk_eq_i32 s0, 0x200
	s_cbranch_scc0 .Lcomb_loop
	s_lshl_b32 s1, s34, 6
	v_bfe_u32 v2, v11, 16, 1
	v_bfe_u32 v3, v10, 16, 1
	v_bfe_u32 v13, v9, 16, 1
	v_bfe_u32 v14, v8, 16, 1
	s_and_b32 s1, s1, 0x3c0
	v_add3_u32 v8, v8, v14, s63
	v_add3_u32 v9, v9, v13, s63
	v_add3_u32 v3, v10, v3, s63
	v_add3_u32 v2, v11, v2, s63
	v_bfe_u32 v10, v6, 16, 1
	v_bfe_u32 v11, v7, 16, 1
	v_bfe_u32 v13, v4, 16, 1
	v_bfe_u32 v14, v5, 16, 1
	v_or_b32_e32 v12, s1, v203
	v_add3_u32 v5, v5, v14, s63
	v_add3_u32 v4, v4, v13, s63
	v_add3_u32 v7, v7, v11, s63
	v_add3_u32 v6, v6, v10, s63
	v_readlane_b32 s10, v244, 19
	s_add_i32 s0, s34, 0xffffddc0
	v_lshrrev_b32_e32 v6, 16, v6
	v_lshrrev_b32_e32 v7, 16, v7
	v_lshrrev_b32_e32 v4, 16, v4
	v_lshrrev_b32_e32 v5, 16, v5
	v_lshlrev_b32_e32 v44, 10, v12
	v_readlane_b32 s11, v244, 20
	v_and_or_b32 v5, v2, s82, v5
	v_and_or_b32 v4, v3, s82, v4
	v_and_or_b32 v3, v9, s82, v7
	v_and_or_b32 v2, v8, s82, v6
	v_lshl_add_u64 v[6:7], s[10:11], 0, v[44:45]
	s_and_b32 s4, s0, 0xffffff00
	v_lshl_add_u64 v[6:7], v[6:7], 0, s[4:5]
	s_and_b32 s4, s0, 0xf0
	v_lshl_add_u64 v[6:7], v[6:7], 0, s[4:5]
	s_mov_b64 s[0:1], 0
	global_store_dwordx4 v[6:7], v[2:5], off

.LBB0_44:
	s_andn2_b64 vcc, exec, s[0:1]
	s_cbranch_vccnz .LBB0_64
	s_and_b32 s0, 0xffff, s81
	s_lshr_b32 s0, s0, 7
	s_bfe_u32 s4, s90, 0x70005
	s_lshl_b32 s1, s0, 18
	s_lshl_b32 s4, s4, 5
	s_or_b32 s1, s4, s1
	v_add_lshl_u32 v44, s1, v80, 2
	v_lshl_add_u64 v[2:3], s[50:51], 0, v[44:45]
	v_add_lshl_u32 v44, s1, v81, 2
	v_lshl_add_u64 v[6:7], s[50:51], 0, v[44:45]
	v_add_lshl_u32 v44, s1, v82, 2
	v_lshl_add_u64 v[8:9], s[50:51], 0, v[44:45]
	v_add_lshl_u32 v44, s1, v83, 2
	v_lshl_add_u64 v[10:11], s[50:51], 0, v[44:45]
	v_add_lshl_u32 v44, s1, v84, 2
	v_lshl_add_u64 v[12:13], s[50:51], 0, v[44:45]
	v_add_lshl_u32 v44, s1, v85, 2
	v_lshl_add_u64 v[14:15], s[50:51], 0, v[44:45]
	v_add_lshl_u32 v44, s1, v86, 2
	s_lshl_b32 s0, s0, 8
	v_lshl_add_u64 v[16:17], s[50:51], 0, v[44:45]
	v_add_lshl_u32 v44, s1, v79, 2
	v_or_b32_e32 v4, s0, v54
	v_mov_b32_e32 v5, v43
	v_lshl_add_u64 v[18:19], s[50:51], 0, v[44:45]
	v_lshl_or_b32 v44, v40, 2, s0
	s_mov_b64 s[10:11], 0
	s_mov_b64 s[88:89], s[48:49]
	v_mov_b32_e32 v22, v78
	v_lshl_add_u64 v[20:21], v[18:19], 0, s[10:11]
	global_load_dword v138, v[20:21], off
	v_lshl_add_u64 v[20:21], v[16:17], 0, s[10:11]
	global_load_dword v139, v[20:21], off
	v_lshl_add_u64 v[20:21], v[14:15], 0, s[10:11]
	global_load_dword v140, v[20:21], off
	v_lshl_add_u64 v[20:21], v[12:13], 0, s[10:11]
	global_load_dword v141, v[20:21], off
	v_lshl_add_u64 v[20:21], v[10:11], 0, s[10:11]
	global_load_dword v142, v[20:21], off
	v_lshl_add_u64 v[20:21], v[8:9], 0, s[10:11]
	global_load_dword v143, v[20:21], off
	v_lshl_add_u64 v[20:21], v[6:7], 0, s[10:11]
	global_load_dword v144, v[20:21], off
	v_lshl_add_u64 v[20:21], v[2:3], 0, s[10:11]
	global_load_dword v145, v[20:21], off
	v_lshl_add_u64 v[24:25], s[88:89], 0, v[4:5]
	global_load_dword v170, v[24:25], off
	global_load_dword v171, v[24:25], off offset:8
	global_load_dword v172, v[24:25], off offset:16
	global_load_dword v173, v[24:25], off offset:24
	global_load_dword v174, v[24:25], off offset:32
	global_load_dword v175, v[24:25], off offset:40
	global_load_dword v176, v[24:25], off offset:48
	global_load_dword v177, v[24:25], off offset:56
	s_add_u32 s10, s10, 0x40000
	s_addc_u32 s11, s11, 0
	s_add_u32 s88, s88, 64
	s_addc_u32 s89, s89, 0
	v_lshl_add_u64 v[20:21], v[18:19], 0, s[10:11]
	global_load_dword v146, v[20:21], off
	v_lshl_add_u64 v[20:21], v[16:17], 0, s[10:11]
	global_load_dword v147, v[20:21], off
	v_lshl_add_u64 v[20:21], v[14:15], 0, s[10:11]
	global_load_dword v148, v[20:21], off
	v_lshl_add_u64 v[20:21], v[12:13], 0, s[10:11]
	global_load_dword v149, v[20:21], off
	v_lshl_add_u64 v[20:21], v[10:11], 0, s[10:11]
	global_load_dword v150, v[20:21], off
	v_lshl_add_u64 v[20:21], v[8:9], 0, s[10:11]
	global_load_dword v151, v[20:21], off
	v_lshl_add_u64 v[20:21], v[6:7], 0, s[10:11]
	global_load_dword v152, v[20:21], off
	v_lshl_add_u64 v[20:21], v[2:3], 0, s[10:11]
	global_load_dword v153, v[20:21], off
	v_lshl_add_u64 v[24:25], s[88:89], 0, v[4:5]
	global_load_dword v178, v[24:25], off
	global_load_dword v179, v[24:25], off offset:8
	global_load_dword v180, v[24:25], off offset:16
	global_load_dword v181, v[24:25], off offset:24
	global_load_dword v182, v[24:25], off offset:32
	global_load_dword v183, v[24:25], off offset:40
	global_load_dword v184, v[24:25], off offset:48
	global_load_dword v185, v[24:25], off offset:56
	s_add_u32 s10, s10, 0x40000
	s_addc_u32 s11, s11, 0
	s_add_u32 s88, s88, 64
	s_addc_u32 s89, s89, 0
	v_lshl_add_u64 v[20:21], v[18:19], 0, s[10:11]
	global_load_dword v154, v[20:21], off
	v_lshl_add_u64 v[20:21], v[16:17], 0, s[10:11]
	global_load_dword v155, v[20:21], off
	v_lshl_add_u64 v[20:21], v[14:15], 0, s[10:11]
	global_load_dword v156, v[20:21], off
	v_lshl_add_u64 v[20:21], v[12:13], 0, s[10:11]
	global_load_dword v157, v[20:21], off
	v_lshl_add_u64 v[20:21], v[10:11], 0, s[10:11]
	global_load_dword v158, v[20:21], off
	v_lshl_add_u64 v[20:21], v[8:9], 0, s[10:11]
	global_load_dword v159, v[20:21], off
	v_lshl_add_u64 v[20:21], v[6:7], 0, s[10:11]
	global_load_dword v160, v[20:21], off
	v_lshl_add_u64 v[20:21], v[2:3], 0, s[10:11]
	global_load_dword v161, v[20:21], off
	v_lshl_add_u64 v[24:25], s[88:89], 0, v[4:5]
	global_load_dword v186, v[24:25], off
	global_load_dword v187, v[24:25], off offset:8
	global_load_dword v188, v[24:25], off offset:16
	global_load_dword v189, v[24:25], off offset:24
	global_load_dword v190, v[24:25], off offset:32
	global_load_dword v191, v[24:25], off offset:40
	global_load_dword v192, v[24:25], off offset:48
	global_load_dword v193, v[24:25], off offset:56
	s_add_u32 s10, s10, 0x40000
	s_addc_u32 s11, s11, 0
	s_add_u32 s88, s88, 64
	s_addc_u32 s89, s89, 0
	v_lshl_add_u64 v[20:21], v[18:19], 0, s[10:11]
	global_load_dword v162, v[20:21], off
	v_lshl_add_u64 v[20:21], v[16:17], 0, s[10:11]
	global_load_dword v163, v[20:21], off
	v_lshl_add_u64 v[20:21], v[14:15], 0, s[10:11]
	global_load_dword v164, v[20:21], off
	v_lshl_add_u64 v[20:21], v[12:13], 0, s[10:11]
	global_load_dword v165, v[20:21], off
	v_lshl_add_u64 v[20:21], v[10:11], 0, s[10:11]
	global_load_dword v166, v[20:21], off
	v_lshl_add_u64 v[20:21], v[8:9], 0, s[10:11]
	global_load_dword v167, v[20:21], off
	v_lshl_add_u64 v[20:21], v[6:7], 0, s[10:11]
	global_load_dword v168, v[20:21], off
	v_lshl_add_u64 v[20:21], v[2:3], 0, s[10:11]
	global_load_dword v169, v[20:21], off
	v_lshl_add_u64 v[24:25], s[88:89], 0, v[4:5]
	global_load_dword v194, v[24:25], off
	global_load_dword v195, v[24:25], off offset:8
	global_load_dword v196, v[24:25], off offset:16
	global_load_dword v197, v[24:25], off offset:24
	global_load_dword v198, v[24:25], off offset:32
	global_load_dword v199, v[24:25], off offset:40
	global_load_dword v200, v[24:25], off offset:48
	global_load_dword v201, v[24:25], off offset:56
	s_add_u32 s10, s10, 0x40000
	s_addc_u32 s11, s11, 0
	s_add_u32 s88, s88, 64
	s_addc_u32 s89, s89, 0
	s_waitcnt vmcnt(0)
	v_mul_f32_e32 v138, v138, v170
	v_mul_f32_e32 v139, v139, v171
	v_mul_f32_e32 v140, v140, v172
	v_mul_f32_e32 v141, v141, v173
	v_mul_f32_e32 v142, v142, v174
	v_mul_f32_e32 v143, v143, v175
	v_mul_f32_e32 v144, v144, v176
	v_mul_f32_e32 v145, v145, v177
	v_mul_f32_e32 v146, v146, v178
	v_mul_f32_e32 v147, v147, v179
	v_mul_f32_e32 v148, v148, v180
	v_mul_f32_e32 v149, v149, v181
	v_mul_f32_e32 v150, v150, v182
	v_mul_f32_e32 v151, v151, v183
	v_mul_f32_e32 v152, v152, v184
	v_mul_f32_e32 v153, v153, v185
	v_mul_f32_e32 v154, v154, v186
	v_mul_f32_e32 v155, v155, v187
	v_mul_f32_e32 v156, v156, v188
	v_mul_f32_e32 v157, v157, v189
	v_mul_f32_e32 v158, v158, v190
	v_mul_f32_e32 v159, v159, v191
	v_mul_f32_e32 v160, v160, v192
	v_mul_f32_e32 v161, v161, v193
	v_mul_f32_e32 v162, v162, v194
	v_mul_f32_e32 v163, v163, v195
	v_mul_f32_e32 v164, v164, v196
	v_mul_f32_e32 v165, v165, v197
	v_mul_f32_e32 v166, v166, v198
	v_mul_f32_e32 v167, v167, v199
	v_mul_f32_e32 v168, v168, v200
	v_mul_f32_e32 v169, v169, v201
	ds_write_b32 v22, v138
	ds_write_b32 v22, v139 offset:264
	ds_write_b32 v22, v140 offset:528
	ds_write_b32 v22, v141 offset:792
	ds_write_b32 v22, v142 offset:1056
	ds_write_b32 v22, v143 offset:1320
	ds_write_b32 v22, v144 offset:1584
	ds_write_b32 v22, v145 offset:1848
	ds_write_b32 v22, v146 offset:2112
	ds_write_b32 v22, v147 offset:2376
	ds_write_b32 v22, v148 offset:2640
	ds_write_b32 v22, v149 offset:2904
	ds_write_b32 v22, v150 offset:3168
	ds_write_b32 v22, v151 offset:3432
	ds_write_b32 v22, v152 offset:3696
	ds_write_b32 v22, v153 offset:3960
	ds_write_b32 v22, v154 offset:4224
	ds_write_b32 v22, v155 offset:4488
	ds_write_b32 v22, v156 offset:4752
	ds_write_b32 v22, v157 offset:5016
	ds_write_b32 v22, v158 offset:5280
	ds_write_b32 v22, v159 offset:5544
	ds_write_b32 v22, v160 offset:5808
	ds_write_b32 v22, v161 offset:6072
	ds_write_b32 v22, v162 offset:6336
	ds_write_b32 v22, v163 offset:6600
	ds_write_b32 v22, v164 offset:6864
	ds_write_b32 v22, v165 offset:7128
	ds_write_b32 v22, v166 offset:7392
	ds_write_b32 v22, v167 offset:7656
	ds_write_b32 v22, v168 offset:7920
	ds_write_b32 v22, v169 offset:8184

.LBB0_70:
	s_andn2_b64 vcc, exec, s[0:1]
	s_cbranch_vccnz .LBB0_74
	s_lshr_b32 s4, s93, 8
	s_lshl_b64 s[0:1], s[4:5], 19
	s_add_u32 s0, s44, s0
	s_addc_u32 s1, s45, s1
	v_lshl_add_u64 v[8:9], s[0:1], 0, v[0:1]
	s_lshl_b32 s0, s93, 12
	s_and_b32 s10, s0, 0xf0000
	s_lshl_b64 s[0:1], s[4:5], 10
	s_add_u32 s0, s10, s0
	s_addc_u32 s1, 0, s1
	s_add_u32 s4, s42, s0
	v_mov_b32_e32 v0, 0
	s_addc_u32 s88, s43, s1
	s_mov_b64 s[0:1], 0
	v_mov_b32_e32 v1, v0
	v_mov_b32_e32 v4, v0
	v_mov_b32_e32 v2, v0
	v_mov_b32_e32 v5, v0
	v_mov_b32_e32 v3, v0
	v_mov_b32_e32 v6, v0
	v_mov_b32_e32 v7, v0
	s_mov_b64 s[12:13], 0x2000
	s_mov_b64 s[14:15], 0x3000
.Latt_loop:
	s_add_u32 s10, s4, s0
	s_addc_u32 s11, s88, s1
	v_lshl_add_u64 v[26:27], v[8:9], 0, s[12:13]
	v_lshl_add_u64 v[28:29], v[8:9], 0, s[14:15]
	global_load_dword v10, v[8:9], off
	global_load_dword v11, v[26:27], off offset:-4096
	global_load_dword v12, v[26:27], off
	global_load_dword v13, v[28:29], off
	v_lshl_add_u64 v[8:9], v[8:9], 0, s[86:87]
	global_load_dwordx4 v[104:107], v45, s[10:11] offset:512
	global_load_dwordx4 v[108:111], v96, s[10:11] offset:512
	global_load_dwordx4 v[112:115], v97, s[10:11] offset:512
	global_load_dwordx4 v[116:119], v98, s[10:11] offset:512
	global_load_dwordx4 v[120:123], v99, s[10:11] offset:512
	global_load_dwordx4 v[124:127], v100, s[10:11] offset:512
	global_load_dwordx4 v[128:131], v101, s[10:11] offset:512
	global_load_dwordx4 v[132:135], v102, s[10:11] offset:512
	v_lshl_add_u64 v[26:27], v[8:9], 0, s[12:13]
	v_lshl_add_u64 v[28:29], v[8:9], 0, s[14:15]
	global_load_dword v14, v[8:9], off
	global_load_dword v15, v[26:27], off offset:-4096
	global_load_dword v16, v[26:27], off
	global_load_dword v17, v[28:29], off
	v_lshl_add_u64 v[8:9], v[8:9], 0, s[86:87]
	global_load_dwordx4 v[138:141], v45, s[10:11] offset:528
	global_load_dwordx4 v[142:145], v96, s[10:11] offset:528
	global_load_dwordx4 v[146:149], v97, s[10:11] offset:528
	global_load_dwordx4 v[150:153], v98, s[10:11] offset:528
	global_load_dwordx4 v[154:157], v99, s[10:11] offset:528
	global_load_dwordx4 v[158:161], v100, s[10:11] offset:528
	global_load_dwordx4 v[162:165], v101, s[10:11] offset:528
	global_load_dwordx4 v[166:169], v102, s[10:11] offset:528
	v_lshl_add_u64 v[26:27], v[8:9], 0, s[12:13]
	v_lshl_add_u64 v[28:29], v[8:9], 0, s[14:15]
	global_load_dword v18, v[8:9], off
	global_load_dword v19, v[26:27], off offset:-4096
	global_load_dword v20, v[26:27], off
	global_load_dword v21, v[28:29], off
	v_lshl_add_u64 v[8:9], v[8:9], 0, s[86:87]
	global_load_dwordx4 v[170:173], v45, s[10:11] offset:544
	global_load_dwordx4 v[174:177], v96, s[10:11] offset:544
	global_load_dwordx4 v[178:181], v97, s[10:11] offset:544
	global_load_dwordx4 v[182:185], v98, s[10:11] offset:544
	global_load_dwordx4 v[186:189], v99, s[10:11] offset:544
	global_load_dwordx4 v[190:193], v100, s[10:11] offset:544
	global_load_dwordx4 v[194:197], v101, s[10:11] offset:544
	global_load_dwordx4 v[198:201], v102, s[10:11] offset:544
	v_lshl_add_u64 v[26:27], v[8:9], 0, s[12:13]
	v_lshl_add_u64 v[28:29], v[8:9], 0, s[14:15]
	global_load_dword v22, v[8:9], off
	global_load_dword v23, v[26:27], off offset:-4096
	global_load_dword v24, v[26:27], off
	global_load_dword v25, v[28:29], off
	v_lshl_add_u64 v[8:9], v[8:9], 0, s[86:87]
	global_load_dwordx4 v[210:213], v45, s[10:11] offset:560
	global_load_dwordx4 v[214:217], v96, s[10:11] offset:560
	global_load_dwordx4 v[218:221], v97, s[10:11] offset:560
	global_load_dwordx4 v[222:225], v98, s[10:11] offset:560
	global_load_dwordx4 v[226:229], v99, s[10:11] offset:560
	global_load_dwordx4 v[230:233], v100, s[10:11] offset:560
	global_load_dwordx4 v[234:237], v101, s[10:11] offset:560
	global_load_dwordx4 v[238:241], v102, s[10:11] offset:560
	s_add_u32 s0, s0, 64
	s_addc_u32 s1, s1, 0
	s_waitcnt vmcnt(36)
	v_fmac_f32_e32 v4, v10, v104
	v_fmac_f32_e32 v2, v10, v108
	v_fmac_f32_e32 v5, v10, v112
	v_fmac_f32_e32 v3, v10, v116
	v_fmac_f32_e32 v0, v10, v120
	v_fmac_f32_e32 v6, v10, v124
	v_fmac_f32_e32 v1, v10, v128
	v_fmac_f32_e32 v7, v10, v132
	v_fmac_f32_e32 v4, v11, v105
	v_fmac_f32_e32 v2, v11, v109
	v_fmac_f32_e32 v5, v11, v113
	v_fmac_f32_e32 v3, v11, v117
	v_fmac_f32_e32 v0, v11, v121
	v_fmac_f32_e32 v6, v11, v125
	v_fmac_f32_e32 v1, v11, v129
	v_fmac_f32_e32 v7, v11, v133
	v_fmac_f32_e32 v4, v12, v106
	v_fmac_f32_e32 v2, v12, v110
	v_fmac_f32_e32 v5, v12, v114
	v_fmac_f32_e32 v3, v12, v118
	v_fmac_f32_e32 v0, v12, v122
	v_fmac_f32_e32 v6, v12, v126
	v_fmac_f32_e32 v1, v12, v130
	v_fmac_f32_e32 v7, v12, v134
	v_fmac_f32_e32 v4, v13, v107
	v_fmac_f32_e32 v2, v13, v111
	v_fmac_f32_e32 v5, v13, v115
	v_fmac_f32_e32 v3, v13, v119
	v_fmac_f32_e32 v0, v13, v123
	v_fmac_f32_e32 v6, v13, v127
	v_fmac_f32_e32 v1, v13, v131
	v_fmac_f32_e32 v7, v13, v135
	s_waitcnt vmcnt(24)
	v_fmac_f32_e32 v4, v14, v138
	v_fmac_f32_e32 v2, v14, v142
	v_fmac_f32_e32 v5, v14, v146
	v_fmac_f32_e32 v3, v14, v150
	v_fmac_f32_e32 v0, v14, v154
	v_fmac_f32_e32 v6, v14, v158
	v_fmac_f32_e32 v1, v14, v162
	v_fmac_f32_e32 v7, v14, v166
	v_fmac_f32_e32 v4, v15, v139
	v_fmac_f32_e32 v2, v15, v143
	v_fmac_f32_e32 v5, v15, v147
	v_fmac_f32_e32 v3, v15, v151
	v_fmac_f32_e32 v0, v15, v155
	v_fmac_f32_e32 v6, v15, v159
	v_fmac_f32_e32 v1, v15, v163
	v_fmac_f32_e32 v7, v15, v167
	v_fmac_f32_e32 v4, v16, v140
	v_fmac_f32_e32 v2, v16, v144
	v_fmac_f32_e32 v5, v16, v148
	v_fmac_f32_e32 v3, v16, v152
	v_fmac_f32_e32 v0, v16, v156
	v_fmac_f32_e32 v6, v16, v160
	v_fmac_f32_e32 v1, v16, v164
	v_fmac_f32_e32 v7, v16, v168
	v_fmac_f32_e32 v4, v17, v141
	v_fmac_f32_e32 v2, v17, v145
	v_fmac_f32_e32 v5, v17, v149
	v_fmac_f32_e32 v3, v17, v153
	v_fmac_f32_e32 v0, v17, v157
	v_fmac_f32_e32 v6, v17, v161
	v_fmac_f32_e32 v1, v17, v165
	v_fmac_f32_e32 v7, v17, v169
	s_waitcnt vmcnt(12)
	v_fmac_f32_e32 v4, v18, v170
	v_fmac_f32_e32 v2, v18, v174
	v_fmac_f32_e32 v5, v18, v178
	v_fmac_f32_e32 v3, v18, v182
	v_fmac_f32_e32 v0, v18, v186
	v_fmac_f32_e32 v6, v18, v190
	v_fmac_f32_e32 v1, v18, v194
	v_fmac_f32_e32 v7, v18, v198
	v_fmac_f32_e32 v4, v19, v171
	v_fmac_f32_e32 v2, v19, v175
	v_fmac_f32_e32 v5, v19, v179
	v_fmac_f32_e32 v3, v19, v183
	v_fmac_f32_e32 v0, v19, v187
	v_fmac_f32_e32 v6, v19, v191
	v_fmac_f32_e32 v1, v19, v195
	v_fmac_f32_e32 v7, v19, v199
	v_fmac_f32_e32 v4, v20, v172
	v_fmac_f32_e32 v2, v20, v176
	v_fmac_f32_e32 v5, v20, v180
	v_fmac_f32_e32 v3, v20, v184
	v_fmac_f32_e32 v0, v20, v188
	v_fmac_f32_e32 v6, v20, v192
	v_fmac_f32_e32 v1, v20, v196
	v_fmac_f32_e32 v7, v20, v200
	v_fmac_f32_e32 v4, v21, v173
	v_fmac_f32_e32 v2, v21, v177
	v_fmac_f32_e32 v5, v21, v181
	v_fmac_f32_e32 v3, v21, v185
	v_fmac_f32_e32 v0, v21, v189
	v_fmac_f32_e32 v6, v21, v193
	v_fmac_f32_e32 v1, v21, v197
	v_fmac_f32_e32 v7, v21, v201
	s_waitcnt vmcnt(0)
	v_fmac_f32_e32 v4, v22, v210
	v_fmac_f32_e32 v2, v22, v214
	v_fmac_f32_e32 v5, v22, v218
	v_fmac_f32_e32 v3, v22, v222
	v_fmac_f32_e32 v0, v22, v226
	v_fmac_f32_e32 v6, v22, v230
	v_fmac_f32_e32 v1, v22, v234
	v_fmac_f32_e32 v7, v22, v238
	v_fmac_f32_e32 v4, v23, v211
	v_fmac_f32_e32 v2, v23, v215
	v_fmac_f32_e32 v5, v23, v219
	v_fmac_f32_e32 v3, v23, v223
	v_fmac_f32_e32 v0, v23, v227
	v_fmac_f32_e32 v6, v23, v231
	v_fmac_f32_e32 v1, v23, v235
	v_fmac_f32_e32 v7, v23, v239
	v_fmac_f32_e32 v4, v24, v212
	v_fmac_f32_e32 v2, v24, v216
	v_fmac_f32_e32 v5, v24, v220
	v_fmac_f32_e32 v3, v24, v224
	v_fmac_f32_e32 v0, v24, v228
	v_fmac_f32_e32 v6, v24, v232
	v_fmac_f32_e32 v1, v24, v236
	v_fmac_f32_e32 v7, v24, v240
	v_fmac_f32_e32 v4, v25, v213
	v_fmac_f32_e32 v2, v25, v217
	v_fmac_f32_e32 v5, v25, v221
	v_fmac_f32_e32 v3, v25, v225
	v_fmac_f32_e32 v0, v25, v229
	v_fmac_f32_e32 v6, v25, v233
	v_fmac_f32_e32 v1, v25, v237
	v_fmac_f32_e32 v7, v25, v241
	s_cmpk_eq_i32 s0, 0x200
	s_cbranch_scc0 .Latt_loop
	s_add_i32 s0, s34, 0xfffff7c0
	s_lshr_b32 s1, s0, 1
	s_and_b32 s1, s1, 0x78
	s_lshl_b32 s4, s1, 2
	v_mov_b32_e32 v12, s4
	global_load_dwordx4 v[8:11], v12, s[40:41]
	s_nop 0
	global_load_dwordx4 v[12:15], v12, s[40:41] offset:16
	s_lshl_b32 s4, s34, 6
	s_and_b32 s10, s4, 0x3c0
	v_or_b32_e32 v16, s10, v203
	v_readlane_b32 s10, v244, 21
	v_lshlrev_b32_e32 v44, 11, v16
	v_readlane_b32 s11, v244, 22
	s_and_b32 s4, s0, 0xffffff00
	s_waitcnt vmcnt(1)
	v_mov_b32_e32 v18, v8
	v_mov_b32_e32 v19, v10
	v_mov_b32_e32 v10, v9
	s_waitcnt vmcnt(0)
	v_mov_b32_e32 v8, v12
	v_mov_b32_e32 v9, v14
	v_mov_b32_e32 v14, v13
	v_pk_mul_f32 v[4:5], v[4:5], v[18:19]
	v_pk_mul_f32 v[0:1], v[0:1], v[8:9]
	v_pk_mul_f32 v[2:3], v[2:3], v[10:11]
	v_pk_mul_f32 v[6:7], v[6:7], v[14:15]
	v_bfe_u32 v12, v4, 16, 1
	v_bfe_u32 v13, v5, 16, 1
	v_bfe_u32 v14, v0, 16, 1
	v_bfe_u32 v15, v1, 16, 1
	v_lshl_add_u64 v[16:17], s[10:11], 0, v[44:45]
	v_bfe_u32 v8, v7, 16, 1
	v_bfe_u32 v9, v6, 16, 1
	v_bfe_u32 v10, v3, 16, 1
	v_bfe_u32 v11, v2, 16, 1
	v_add3_u32 v1, v1, v15, s63
	v_add3_u32 v0, v0, v14, s63
	v_add3_u32 v5, v5, v13, s63
	v_add3_u32 v4, v4, v12, s63
	v_lshl_add_u64 v[16:17], v[16:17], 0, s[4:5]
	s_lshl_b32 s4, s1, 1
	v_add3_u32 v11, v2, v11, s63
	v_add3_u32 v10, v3, v10, s63
	v_add3_u32 v2, v6, v9, s63
	v_add3_u32 v3, v7, v8, s63
	v_lshrrev_b32_e32 v4, 16, v4
	v_lshrrev_b32_e32 v5, 16, v5
	v_lshrrev_b32_e32 v0, 16, v0
	v_lshrrev_b32_e32 v1, 16, v1
	v_and_or_b32 v3, v3, s82, v1
	v_and_or_b32 v2, v2, s82, v0
	v_and_or_b32 v1, v10, s82, v5
	v_and_or_b32 v0, v11, s82, v4
	v_lshl_add_u64 v[4:5], v[16:17], 0, s[4:5]
	global_store_dwordx4 v[4:5], v[0:3], off

.LBB0_108:
	s_or_b64 exec, exec, s[0:1]
	v_readlane_b32 s12, v244, 0
	s_lshl_b32 s0, s88, 6
	v_readlane_b32 s18, v244, 6
	v_readlane_b32 s19, v244, 7
	v_cmp_lt_i32_e32 vcc, -1, v44
	v_or_b32_e32 v2, s0, v40
	v_lshl_add_u64 v[0:1], v[44:45], 2, s[18:19]
	s_mov_b32 s1, 0
	v_mov_b32_e32 v3, v78
	v_readlane_b32 s13, v244, 1
	v_readlane_b32 s14, v244, 2
	v_readlane_b32 s15, v244, 3
	v_readlane_b32 s16, v244, 4
	v_readlane_b32 s17, v244, 5
	v_readlane_b32 s20, v244, 8
	v_readlane_b32 s21, v244, 9
	v_readlane_b32 s22, v244, 10
	v_readlane_b32 s23, v244, 11
	v_readlane_b32 s24, v244, 12
	v_readlane_b32 s25, v244, 13
	v_readlane_b32 s26, v244, 14
	v_readlane_b32 s27, v244, 15
	v_mov_b32_e32 v138, 0
	v_mov_b32_e32 v139, 0
	v_mov_b32_e32 v140, 0
	v_mov_b32_e32 v141, 0
	v_mov_b32_e32 v142, 0
	v_mov_b32_e32 v143, 0
	v_mov_b32_e32 v144, 0
	v_mov_b32_e32 v145, 0
	v_mov_b32_e32 v146, 0
	v_mov_b32_e32 v147, 0
	v_mov_b32_e32 v148, 0
	v_mov_b32_e32 v149, 0
	v_mov_b32_e32 v150, 0
	v_mov_b32_e32 v151, 0
	v_mov_b32_e32 v152, 0
	v_mov_b32_e32 v153, 0
	v_mov_b32_e32 v154, 0
	v_mov_b32_e32 v155, 0
	v_mov_b32_e32 v156, 0
	v_mov_b32_e32 v157, 0
	v_mov_b32_e32 v158, 0
	v_mov_b32_e32 v159, 0
	v_mov_b32_e32 v160, 0
	v_mov_b32_e32 v161, 0
	v_mov_b32_e32 v162, 0
	v_mov_b32_e32 v163, 0
	v_mov_b32_e32 v164, 0
	v_mov_b32_e32 v165, 0
	v_mov_b32_e32 v166, 0
	v_mov_b32_e32 v167, 0
	v_mov_b32_e32 v168, 0
	v_mov_b32_e32 v169, 0
	s_and_saveexec_b64 s[10:11], vcc
	v_mov_b32_e32 v5, v2
	v_mad_i64_i32 v[6:7], s[88:89], v5, s64, v[0:1]
	global_load_dword v138, v[6:7], off
	v_add_u32_e32 v5, 2, v2
	v_mad_i64_i32 v[6:7], s[88:89], v5, s64, v[0:1]
	global_load_dword v139, v[6:7], off
	v_add_u32_e32 v5, 4, v2
	v_mad_i64_i32 v[6:7], s[88:89], v5, s64, v[0:1]
	global_load_dword v140, v[6:7], off
	v_add_u32_e32 v5, 6, v2
	v_mad_i64_i32 v[6:7], s[88:89], v5, s64, v[0:1]
	global_load_dword v141, v[6:7], off
	v_add_u32_e32 v5, 8, v2
	v_mad_i64_i32 v[6:7], s[88:89], v5, s64, v[0:1]
	global_load_dword v142, v[6:7], off
	v_add_u32_e32 v5, 10, v2
	v_mad_i64_i32 v[6:7], s[88:89], v5, s64, v[0:1]
	global_load_dword v143, v[6:7], off
	v_add_u32_e32 v5, 12, v2
	v_mad_i64_i32 v[6:7], s[88:89], v5, s64, v[0:1]
	global_load_dword v144, v[6:7], off
	v_add_u32_e32 v5, 14, v2
	v_mad_i64_i32 v[6:7], s[88:89], v5, s64, v[0:1]
	global_load_dword v145, v[6:7], off
	v_add_u32_e32 v5, 16, v2
	v_mad_i64_i32 v[6:7], s[88:89], v5, s64, v[0:1]
	global_load_dword v146, v[6:7], off
	v_add_u32_e32 v5, 18, v2
	v_mad_i64_i32 v[6:7], s[88:89], v5, s64, v[0:1]
	global_load_dword v147, v[6:7], off
	v_add_u32_e32 v5, 20, v2
	v_mad_i64_i32 v[6:7], s[88:89], v5, s64, v[0:1]
	global_load_dword v148, v[6:7], off
	v_add_u32_e32 v5, 22, v2
	v_mad_i64_i32 v[6:7], s[88:89], v5, s64, v[0:1]
	global_load_dword v149, v[6:7], off
	v_add_u32_e32 v5, 24, v2
	v_mad_i64_i32 v[6:7], s[88:89], v5, s64, v[0:1]
	global_load_dword v150, v[6:7], off
	v_add_u32_e32 v5, 26, v2
	v_mad_i64_i32 v[6:7], s[88:89], v5, s64, v[0:1]
	global_load_dword v151, v[6:7], off
	v_add_u32_e32 v5, 28, v2
	v_mad_i64_i32 v[6:7], s[88:89], v5, s64, v[0:1]
	global_load_dword v152, v[6:7], off
	v_add_u32_e32 v5, 30, v2
	v_mad_i64_i32 v[6:7], s[88:89], v5, s64, v[0:1]
	global_load_dword v153, v[6:7], off
	v_add_u32_e32 v5, 32, v2
	v_mad_i64_i32 v[6:7], s[88:89], v5, s64, v[0:1]
	global_load_dword v154, v[6:7], off
	v_add_u32_e32 v5, 34, v2
	v_mad_i64_i32 v[6:7], s[88:89], v5, s64, v[0:1]
	global_load_dword v155, v[6:7], off
	v_add_u32_e32 v5, 36, v2
	v_mad_i64_i32 v[6:7], s[88:89], v5, s64, v[0:1]
	global_load_dword v156, v[6:7], off
	v_add_u32_e32 v5, 38, v2
	v_mad_i64_i32 v[6:7], s[88:89], v5, s64, v[0:1]
	global_load_dword v157, v[6:7], off
	v_add_u32_e32 v5, 40, v2
	v_mad_i64_i32 v[6:7], s[88:89], v5, s64, v[0:1]
	global_load_dword v158, v[6:7], off
	v_add_u32_e32 v5, 42, v2
	v_mad_i64_i32 v[6:7], s[88:89], v5, s64, v[0:1]
	global_load_dword v159, v[6:7], off
	v_add_u32_e32 v5, 44, v2
	v_mad_i64_i32 v[6:7], s[88:89], v5, s64, v[0:1]
	global_load_dword v160, v[6:7], off
	v_add_u32_e32 v5, 46, v2
	v_mad_i64_i32 v[6:7], s[88:89], v5, s64, v[0:1]
	global_load_dword v161, v[6:7], off
	v_add_u32_e32 v5, 48, v2
	v_mad_i64_i32 v[6:7], s[88:89], v5, s64, v[0:1]
	global_load_dword v162, v[6:7], off
	v_add_u32_e32 v5, 50, v2
	v_mad_i64_i32 v[6:7], s[88:89], v5, s64, v[0:1]
	global_load_dword v163, v[6:7], off
	v_add_u32_e32 v5, 52, v2
	v_mad_i64_i32 v[6:7], s[88:89], v5, s64, v[0:1]
	global_load_dword v164, v[6:7], off
	v_add_u32_e32 v5, 54, v2
	v_mad_i64_i32 v[6:7], s[88:89], v5, s64, v[0:1]
	global_load_dword v165, v[6:7], off
	v_add_u32_e32 v5, 56, v2
	v_mad_i64_i32 v[6:7], s[88:89], v5, s64, v[0:1]
	global_load_dword v166, v[6:7], off
	v_add_u32_e32 v5, 58, v2
	v_mad_i64_i32 v[6:7], s[88:89], v5, s64, v[0:1]
	global_load_dword v167, v[6:7], off
	v_add_u32_e32 v5, 60, v2
	v_mad_i64_i32 v[6:7], s[88:89], v5, s64, v[0:1]
	global_load_dword v168, v[6:7], off
	v_add_u32_e32 v5, 62, v2
	v_mad_i64_i32 v[6:7], s[88:89], v5, s64, v[0:1]
	global_load_dword v169, v[6:7], off
	s_or_b64 exec, exec, s[10:11]
	s_waitcnt vmcnt(0)
	ds_write_b32 v3, v138
	ds_write_b32 v3, v139 offset:264
	ds_write_b32 v3, v140 offset:528
	ds_write_b32 v3, v141 offset:792
	ds_write_b32 v3, v142 offset:1056
	ds_write_b32 v3, v143 offset:1320
	ds_write_b32 v3, v144 offset:1584
	ds_write_b32 v3, v145 offset:1848
	ds_write_b32 v3, v146 offset:2112
	ds_write_b32 v3, v147 offset:2376
	ds_write_b32 v3, v148 offset:2640
	ds_write_b32 v3, v149 offset:2904
	ds_write_b32 v3, v150 offset:3168
	ds_write_b32 v3, v151 offset:3432
	ds_write_b32 v3, v152 offset:3696
	ds_write_b32 v3, v153 offset:3960
	ds_write_b32 v3, v154 offset:4224
	ds_write_b32 v3, v155 offset:4488
	ds_write_b32 v3, v156 offset:4752
	ds_write_b32 v3, v157 offset:5016
	ds_write_b32 v3, v158 offset:5280
	ds_write_b32 v3, v159 offset:5544
	ds_write_b32 v3, v160 offset:5808
	ds_write_b32 v3, v161 offset:6072
	ds_write_b32 v3, v162 offset:6336
	ds_write_b32 v3, v163 offset:6600
	ds_write_b32 v3, v164 offset:6864
	ds_write_b32 v3, v165 offset:7128
	ds_write_b32 v3, v166 offset:7392
	ds_write_b32 v3, v167 offset:7656
	ds_write_b32 v3, v168 offset:7920
	ds_write_b32 v3, v169 offset:8184
	s_branch .LBB0_27

.LBB0_127:
	s_mov_b64 s[12:13], s[94:95]
	v_readfirstlane_b32 s0, v209
	s_nop 1
	s_bitcmp1_b32 s0, 6
	s_cbranch_scc1 .LBB0_138
	v_or_b32_e32 v0, s70, v203
	s_mov_b32 s0, 0x200000
	s_mov_b64 s[12:13], s[94:95]
	v_cmp_gt_i32_e32 vcc, s0, v0
	s_and_saveexec_b64 s[18:19], vcc
	s_cbranch_execz .LBB0_138
	v_and_b32_e32 v1, 31, v209
	v_sub_u32_e32 v1, 0, v1
	s_mov_b32 s0, 0x979a371
	v_cvt_f64_i32_e32 v[2:3], v1
	s_mov_b32 s1, 0x3fda934f
	v_mul_f64 v[2:3], v[2:3], s[0:1]
	v_rndne_f64_e32 v[4:5], v[2:3]
	s_mov_b32 s0, 0x3b39803f
	v_add_f64 v[6:7], v[2:3], -v[4:5]
	s_mov_b32 s1, 0x3c7abc9e
	v_mul_f64 v[8:9], v[6:7], s[0:1]
	s_mov_b32 s0, 0xfefa39ef
	s_mov_b32 s1, 0x3fe62e42
	v_fmac_f64_e32 v[8:9], s[0:1], v[6:7]
	s_mov_b32 s0, 0x6a5dcb37
	v_mov_b32_e32 v6, 0xfca7ab0c
	v_mov_b32_e32 v7, 0x3e928af3
	s_mov_b32 s1, 0x3e5ade15
	v_fmac_f64_e32 v[6:7], s[0:1], v[8:9]
	v_mov_b32_e32 v10, 0x623fde64
	v_mov_b32_e32 v11, 0x3ec71dee
	v_fmac_f64_e32 v[10:11], v[8:9], v[6:7]
	v_mov_b32_e32 v6, 0x7c89e6b0
	v_mov_b32_e32 v7, 0x3efa0199
	v_fmac_f64_e32 v[6:7], v[8:9], v[10:11]
	v_mov_b32_e32 v10, 0x14761f6e
	v_mov_b32_e32 v11, 0x3f2a01a0
	v_fmac_f64_e32 v[10:11], v[8:9], v[6:7]
	v_mov_b32_e32 v6, 0x1852b7b0
	v_mov_b32_e32 v7, 0x3f56c16c
	v_fmac_f64_e32 v[6:7], v[8:9], v[10:11]
	v_mov_b32_e32 v10, 0x11122322
	v_mov_b32_e32 v11, 0x3f811111
	v_fmac_f64_e32 v[10:11], v[8:9], v[6:7]
	v_mov_b32_e32 v6, 0x555502a1
	v_mov_b32_e32 v7, 0x3fa55555
	v_fmac_f64_e32 v[6:7], v[8:9], v[10:11]
	v_mov_b32_e32 v10, 0x55555511
	v_mov_b32_e32 v11, 0x3fc55555
	v_fmac_f64_e32 v[10:11], v[8:9], v[6:7]
	v_mov_b32_e32 v6, 11
	v_mov_b32_e32 v7, 0x3fe00000
	s_mov_b32 s0, 0
	v_fmac_f64_e32 v[6:7], v[8:9], v[10:11]
	s_mov_b32 s1, 0x40900000
	v_fma_f64 v[6:7], v[8:9], v[6:7], 1.0
	v_cmp_nlt_f64_e32 vcc, s[0:1], v[2:3]
	s_mov_b32 s0, 0
	v_fma_f64 v[6:7], v[8:9], v[6:7], 1.0
	v_cvt_i32_f64_e32 v1, v[4:5]
	s_mov_b32 s1, 0xc090cc00
	v_ldexp_f64 v[4:5], v[6:7], v1
	v_mov_b32_e32 v1, 0x7ff00000
	v_cmp_ngt_f64_e64 s[0:1], s[0:1], v[2:3]
	v_cndmask_b32_e32 v1, v1, v5, vcc
	s_and_b64 vcc, s[0:1], vcc
	s_lshl_b32 s22, s30, 8
	v_cndmask_b32_e64 v3, 0, v1, s[0:1]
	v_cndmask_b32_e32 v2, 0, v4, vcc
	v_ashrrev_i32_e32 v1, 31, v0
	v_cvt_f32_f64_e32 v6, v[2:3]
	v_lshl_add_u64 v[2:3], v[0:1], 2, s[58:59]
	s_mov_b64 s[0:1], 0x3a800000
	s_ashr_i32 s23, s22, 31
	s_mov_b32 s26, 0x6dc9c883
	s_mov_b32 s36, 0x54442d18
	v_lshl_add_u64 v[2:3], v[2:3], 0, s[0:1]
	s_lshl_b64 s[10:11], s[22:23], 2
	s_mov_b64 s[24:25], 0
	s_mov_b32 s27, 0x3fc45f30
	s_mov_b32 s37, 0x401921fb
	s_brev_b32 s23, 18
	s_mov_b32 s34, 0xfe5163ab
	v_mov_b32_e32 v5, 0
	s_mov_b32 s35, 0x3c439041
	s_mov_b32 s40, 0xdb629599
	s_mov_b32 s41, 0xf534ddc0
	s_mov_b32 s42, 0xfc2757d1
	s_mov_b32 s43, 0x4e441529
	s_mov_b32 s44, 0xa2f9836e
	s_mov_b32 s45, 0x3fc90fda
	s_mov_b32 s46, 0x3f22f983
	s_mov_b32 s47, 0xbfc90fda
	v_mov_b32_e32 v1, 0x3c0881c4
	v_mov_b32_e32 v7, 0xbab64f3b
	s_brev_b32 s48, 1
	s_movk_i32 s49, 0x1f8
	s_mov_b32 s50, 0x1fffff
	v_not_b32_e32 v8, 63
	v_not_b32_e32 v9, 31
	v_mov_b32_e32 v10, 0x7fc00000
	s_branch .LBB0_130

.Lxn_begin:
	v_readlane_b32 s10, v244, 17
	v_readlane_b32 s12, v244, 0
	v_readlane_b32 s13, v244, 1
	v_readlane_b32 s16, v244, 4
	v_readlane_b32 s17, v244, 5
	v_lshlrev_b32_e32 v32, 5, v203
	v_mov_b32_e32 v33, 0
	v_lshlrev_b32_e32 v35, 4, v203
	v_mov_b32_e32 v34, 0x358637bd
	v_lshlrev_b32_e32 v0, 2, v203
	v_xor_b32_e32 v42, 4, v0
	v_xor_b32_e32 v43, 8, v0
	v_xor_b32_e32 v44, 16, v0
	v_xor_b32_e32 v45, 32, v0
	v_xor_b32_e32 v46, 64, v0
	v_xor_b32_e32 v47, 0x80, v0
	s_mov_b32 s5, 0
	s_nop 3
	v_writelane_b32 v244, s5, 18
	global_load_dwordx4 v[60:63], v32, s[16:17]
	global_load_dwordx4 v[64:67], v32, s[16:17] offset:16
	global_load_dwordx4 v[68:71], v32, s[16:17] offset:2048
	global_load_dwordx4 v[72:75], v32, s[16:17] offset:2064
	s_lshl_b32 s4, s10, 12
	s_add_u32 s4, s12, s4
	s_addc_u32 s5, s13, 0
	s_add_u32 s4, s4, 0x1000
	s_addc_u32 s5, s5, 0
	s_mov_b32 s6, s72
	s_mov_b32 s7, 0
	s_lshl_b64 s[6:7], s[6:7], 12
	s_lshl_b64 s[8:9], s[6:7], 1
	s_lshr_b64 s[22:23], s[6:7], 1
	v_lshl_add_u64 v[36:37], s[4:5], 0, v[32:33]
	v_lshl_add_u64 v[38:39], v[36:37], 0, s[6:7]
	s_lshl_b32 s4, s10, 11
	s_add_u32 s4, s60, s4
	s_addc_u32 s5, s61, 0
	s_add_u32 s4, s4, 0x800
	s_addc_u32 s5, s5, 0
	v_mov_b32_e32 v0, v35
	v_mov_b32_e32 v1, 0
	v_lshl_add_u64 v[108:109], s[4:5], 0, v[0:1]
	v_lshl_add_u64 v[110:111], v[108:109], 0, s[22:23]
	s_lshl_b32 s4, s10, 2
	s_add_u32 s14, s58, 0x1f00000
	s_addc_u32 s15, s59, 0
	s_add_u32 s14, s14, s4
	s_addc_u32 s15, s15, 0
	s_lshl_b32 s4, s72, 2
	s_add_u32 s18, s14, s4
	s_addc_u32 s19, s15, 0
	s_lshl_b32 s26, s72, 3
	s_mov_b32 s24, s10
	s_lshl_b32 s25, s72, 1

.Lxn_end:
	s_lshl_b32 s70, s10, 5
	s_branch .LBB0_127
